# stack: DMA scan v2 + prep step-1 load reordering + up-GEMM epilogue second-half row-scale loads issued early
# baseline (speedup 1.0000x reference)
; #define PG8_LAS __attribute__((address_space(3)))
;     __device__ __forceinline__ void operator()(f32x4 (&acc)[2][2][4][2], const pg8::Unit& u, int wr, int wc, int fr, int fq) const {
;         const int colj = u.pn * 128 + wc * 32 + 8 * fq;
;         PG8_LAS unsigned char* wl = WL + (wr * 4 + wc) * 1024;
;         {
;             const int l = fq * 16 + fr, p = l >> 4, bj = (l >> 3) & 1, c4 = (l & 7) * 4;
;             const float* srcp = (p < 3 ? FW + p * NUP : FB) + bj * DFF + u.pn * 128 + wc * 32 + c4;
;             *(PG8_LAS f32x4*)(wl + l * 16) = *(const f32x4*)srcp;
;         }
; #pragma unroll
;         for (int ai = 0; ai < 2; ++ai) {
;             const int tb = u.pm * 256 + ai * 128 + wr * 64 + 4 * fr;
;             float rstd[4];
; #pragma unroll
;             for (int m = 0; m < 4; ++m) { const f32x4 sv = *(const f32x4*)(SS + (size_t)(tb + m) * 16 + 4 * fq); float s = (sv[0] + sv[1]) + (sv[2] + sv[3]); s += __shfl_xor(s, 16); s += __shfl_xor(s, 32);
;                 rstd[m] = rsqrtf(s * (1.0f / 1024.0f) + EPS); }
.LBB0_748:
	v_lshl_add_u32 v148, s34, 8, v187
	v_ashrrev_i32_e32 v149, 31, v148
	v_lshlrev_b64 v[150:151], 6, v[148:149]
	v_lshl_add_u64 v[154:155], v[138:139], 0, v[150:151]
	v_or_b32_e32 v150, 1, v148
	v_ashrrev_i32_e32 v151, 31, v150
	v_lshlrev_b64 v[156:157], 6, v[150:151]
	v_lshl_add_u64 v[156:157], v[138:139], 0, v[156:157]
	global_load_dwordx4 v[160:163], v[154:155], off
	global_load_dwordx4 v[164:167], v[156:157], off
	v_or_b32_e32 v154, 2, v148
	v_ashrrev_i32_e32 v155, 31, v154
	v_lshlrev_b64 v[156:157], 6, v[154:155]
	v_lshl_add_u64 v[156:157], v[138:139], 0, v[156:157]
	global_load_dwordx4 v[172:175], v[156:157], off
	v_or_b32_e32 v156, 3, v148
	v_ashrrev_i32_e32 v157, 31, v156
	v_lshlrev_b64 v[158:159], 6, v[156:157]
	v_lshl_add_u64 v[158:159], v[138:139], 0, v[158:159]
	global_load_dwordx4 v[176:179], v[158:159], off
	s_lshl_b32 s8, s66, 7
	s_ashr_i32 s9, s8, 31
	v_lshl_add_u64 v[158:159], s[8:9], 2, v[136:137]
	global_load_dwordx4 v[180:183], v[158:159], off
	v_add_u32_e32 v250, 0x80, v148
	v_ashrrev_i32_e32 v251, 31, v250
	v_lshlrev_b64 v[246:247], 6, v[250:251]
	v_lshl_add_u64 v[246:247], v[138:139], 0, v[246:247]
	global_load_dwordx4 v[230:233], v[246:247], off
	v_add_u32_e32 v250, 0x81, v148
	v_ashrrev_i32_e32 v251, 31, v250
	v_lshlrev_b64 v[246:247], 6, v[250:251]
	v_lshl_add_u64 v[246:247], v[138:139], 0, v[246:247]
	global_load_dwordx4 v[234:237], v[246:247], off
	v_add_u32_e32 v250, 0x82, v148
	v_ashrrev_i32_e32 v251, 31, v250
	v_lshlrev_b64 v[246:247], 6, v[250:251]
	v_lshl_add_u64 v[246:247], v[138:139], 0, v[246:247]
	global_load_dwordx4 v[238:241], v[246:247], off
	v_add_u32_e32 v250, 0x83, v148
	v_ashrrev_i32_e32 v251, 31, v250
	v_lshlrev_b64 v[246:247], 6, v[250:251]
	v_lshl_add_u64 v[246:247], v[138:139], 0, v[246:247]
	global_load_dwordx4 v[242:245], v[246:247], off
	v_and_b32_e32 v151, 64, v194
	v_xor_b32_e32 v149, 16, v194
	v_add_u32_e32 v151, 64, v151
	v_cmp_lt_i32_e32 vcc, v149, v151
	v_xor_b32_e32 v155, 32, v194
	v_mov_b64_e32 v[184:185], s[38:39]
	v_cndmask_b32_e32 v149, v194, v149, vcc
	v_lshlrev_b32_e32 v149, 2, v149
	v_cmp_lt_i32_e32 vcc, v155, v151
	v_or_b32_e32 v158, s8, v186
	v_ashrrev_i32_e32 v159, 31, v158
	v_cndmask_b32_e32 v151, v194, v155, vcc
	v_lshlrev_b32_e32 v151, 2, v151
	s_waitcnt vmcnt(4)
	v_mov_b32_e32 v196, v161
	v_mov_b32_e32 v197, v162
	v_mov_b32_e32 v161, v163
	v_mov_b32_e32 v162, v165
	v_mov_b32_e32 v163, v166
	v_mov_b32_e32 v165, v167
	v_mov_b32_e32 v166, v173
	v_mov_b32_e32 v167, v174
	v_mov_b32_e32 v173, v175
	v_pk_add_f32 v[160:161], v[196:197], v[160:161]
	v_pk_add_f32 v[162:163], v[162:163], v[164:165]
	v_mov_b32_e32 v174, v177
	v_mov_b32_e32 v175, v178
	v_mov_b32_e32 v177, v179
	v_pk_add_f32 v[166:167], v[166:167], v[172:173]
	v_pk_add_f32 v[172:173], v[174:175], v[176:177]
	v_mov_b32_e32 v165, v160
	v_mov_b32_e32 v164, v162
	v_mov_b32_e32 v160, v163
	v_mov_b32_e32 v162, v172
	v_mov_b32_e32 v163, v166
	v_mov_b32_e32 v166, v173
	v_pk_add_f32 v[160:161], v[164:165], v[160:161]
	v_pk_add_f32 v[162:163], v[162:163], v[166:167]
	ds_bpermute_b32 v165, v149, v161
	ds_bpermute_b32 v164, v149, v160
	ds_bpermute_b32 v167, v149, v163
	ds_bpermute_b32 v166, v149, v162
	ds_write_b128 v193, v[180:183]
	s_waitcnt lgkmcnt(3)
	v_pk_add_f32 v[172:173], v[160:161], v[164:165]
	ds_bpermute_b32 v197, v151, v173
	s_waitcnt lgkmcnt(2)
	v_pk_add_f32 v[174:175], v[162:163], v[166:167]
	ds_bpermute_b32 v196, v151, v172
	ds_bpermute_b32 v199, v151, v175
	ds_bpermute_b32 v198, v151, v174
	ds_read_b128 v[160:163], v195
	ds_read_b128 v[164:167], v195 offset:256
	ds_read_b128 v[176:179], v195 offset:512
	ds_read_b128 v[180:183], v195 offset:768
	s_waitcnt lgkmcnt(6)
	v_pk_add_f32 v[172:173], v[172:173], v[196:197]
	s_nop 0
	v_pk_fma_f32 v[172:173], v[172:173], s[24:25], v[184:185] op_sel_hi:[1,0,0]
	s_waitcnt lgkmcnt(4)
	v_pk_add_f32 v[174:175], v[174:175], v[198:199]
	v_mul_f32_e32 v155, 0x4b800000, v173
	v_pk_fma_f32 v[174:175], v[174:175], s[24:25], v[184:185] op_sel_hi:[1,0,0]
	v_cmp_gt_f32_e32 vcc, s63, v173
	v_mul_f32_e32 v168, 0x4b800000, v175
	v_mul_f32_e32 v170, 0x4b800000, v174
	v_cmp_gt_f32_e64 s[10:11], s63, v175
	v_cmp_gt_f32_e64 s[12:13], s63, v174
	v_cndmask_b32_e32 v155, v173, v155, vcc
	v_cndmask_b32_e64 v168, v175, v168, s[10:11]
	v_cndmask_b32_e64 v170, v174, v170, s[12:13]
	v_rsq_f32_e32 v155, v155
	v_rsq_f32_e32 v168, v168
	v_rsq_f32_e32 v173, v170
	v_mul_f32_e32 v157, 0x4b800000, v172
	v_cmp_gt_f32_e64 s[8:9], s63, v172
	v_mul_f32_e32 v170, 0x45800000, v155
	v_mul_f32_e32 v175, 0x45800000, v168
	v_cndmask_b32_e64 v157, v172, v157, s[8:9]
	v_mul_f32_e32 v184, 0x45800000, v173
	v_rsq_f32_e32 v157, v157
	v_cndmask_b32_e32 v174, v155, v170, vcc
	v_cndmask_b32_e64 v170, v168, v175, s[10:11]
	v_cndmask_b32_e64 v168, v173, v184, s[12:13]
	v_pk_mul_f32 v[124:125], v[124:125], v[174:175] op_sel_hi:[1,0]
	v_pk_mul_f32 v[112:113], v[112:113], v[168:169] op_sel_hi:[1,0]
	v_pk_mul_f32 v[116:117], v[116:117], v[170:171] op_sel_hi:[1,0]
	s_waitcnt lgkmcnt(0)
; #define PG8_LAS __attribute__((address_space(3)))
; __device__ __forceinline__ float row_up1(float v) { return dpp_mov<0x111>(v); }
; __device__ __forceinline__ float siluf_(float x) { return x * __builtin_amdgcn_rcpf(1.0f + __builtin_amdgcn_exp2f(x * -1.4426950408889634f)); }
;     __device__ __forceinline__ void operator()(f32x4 (&acc)[2][2][4][2], const pg8::Unit& u, int wr, int wc, int fr, int fq) const {
;     ...
;             for (int n = 0; n < 2; ++n) {
;                 f32x4 g[4];
;                 {   const PG8_LAS unsigned char* wq = wl + (8 * fq + 4 * n) * 4;
;                     const f32x4 w0 = *(const PG8_LAS f32x4*)(wq), w1 = *(const PG8_LAS f32x4*)(wq + 256), w2 = *(const PG8_LAS f32x4*)(wq + 512), bb = *(const PG8_LAS f32x4*)(wq + 768);
;                     const f32x4 x0 = acc[ai][0][0][n] * rstd[0], x1 = acc[ai][0][1][n] * rstd[1], x2 = acc[ai][0][2][n] * rstd[2], x3 = acc[ai][0][3][n] * rstd[3];
;                     acc[ai][0][0][n] = x0; acc[ai][0][1][n] = x1; acc[ai][0][2][n] = x2; acc[ai][0][3][n] = x3;
;                     f32x4 p1, p2;
; #pragma unroll
;                     for (int c = 0; c < 4; ++c) { p1[c] = row_up1(x3[c]); p2[c] = row_up1(x2[c]); }
;                     g[0] = bb + w2 * x0 + w1 * p1 + w0 * p2; g[1] = bb + w2 * x1 + w1 * x0 + w0 * p1;
;                     g[2] = bb + w2 * x2 + w1 * x1 + w0 * x0; g[3] = bb + w2 * x3 + w1 * x2 + w0 * x1;
; #pragma unroll
;                     for (int m = 0; m < 4; ++m)
; #pragma unroll
;                         for (int c = 0; c < 4; ++c) g[m][c] = siluf_(g[m][c]);
;                 }
;                 __builtin_amdgcn_sched_barrier(0);
;                 {   const PG8_LAS unsigned char* wq = wl + 128 + (8 * fq + 4 * n) * 4;
;                     const f32x4 w0 = *(const PG8_LAS f32x4*)(wq), w1 = *(const PG8_LAS f32x4*)(wq + 256), w2 = *(const PG8_LAS f32x4*)(wq + 512), bb = *(const PG8_LAS f32x4*)(wq + 768);
;                     const f32x4 x0 = acc[ai][1][0][n] * rstd[0], x1 = acc[ai][1][1][n] * rstd[1], x2 = acc[ai][1][2][n] * rstd[2], x3 = acc[ai][1][3][n] * rstd[3];
	v_pk_fma_f32 v[204:205], v[176:177], v[124:125], v[180:181]
	v_mov_b32_dpp v184, v112 row_shr:1 row_mask:0xf bank_mask:0xf bound_ctrl:1
	v_mov_b32_dpp v185, v113 row_shr:1 row_mask:0xf bank_mask:0xf bound_ctrl:1
	v_mov_b32_dpp v196, v116 row_shr:1 row_mask:0xf bank_mask:0xf bound_ctrl:1
	v_mov_b32_dpp v197, v117 row_shr:1 row_mask:0xf bank_mask:0xf bound_ctrl:1
	v_pk_fma_f32 v[204:205], v[164:165], v[184:185], v[204:205]
	v_mul_f32_e32 v172, 0x45800000, v157
	v_pk_fma_f32 v[196:197], v[160:161], v[196:197], v[204:205]
	v_cndmask_b32_e64 v172, v157, v172, s[8:9]
	v_mul_f32_e32 v155, 0xbfb8aa3b, v196
	v_pk_mul_f32 v[126:127], v[126:127], v[174:175] op_sel_hi:[1,0]
	v_pk_mul_f32 v[120:121], v[120:121], v[172:173] op_sel_hi:[1,0]
	v_pk_mul_f32 v[114:115], v[114:115], v[168:169] op_sel_hi:[1,0]
	v_exp_f32_e32 v155, v155
	v_mul_f32_e32 v157, 0xbfb8aa3b, v197
	v_pk_mul_f32 v[118:119], v[118:119], v[170:171] op_sel_hi:[1,0]
	v_mov_b32_dpp v198, v114 row_shr:1 row_mask:0xf bank_mask:0xf bound_ctrl:1
	v_mov_b32_dpp v199, v115 row_shr:1 row_mask:0xf bank_mask:0xf bound_ctrl:1
	v_pk_fma_f32 v[202:203], v[178:179], v[126:127], v[182:183]
	v_pk_fma_f32 v[204:205], v[176:177], v[120:121], v[180:181]
	v_exp_f32_e32 v157, v157
	v_pk_mul_f32 v[122:123], v[122:123], v[172:173] op_sel_hi:[1,0]
	v_mov_b32_dpp v200, v118 row_shr:1 row_mask:0xf bank_mask:0xf bound_ctrl:1
	v_mov_b32_dpp v201, v119 row_shr:1 row_mask:0xf bank_mask:0xf bound_ctrl:1
	v_pk_fma_f32 v[202:203], v[166:167], v[198:199], v[202:203]
	v_pk_fma_f32 v[204:205], v[164:165], v[124:125], v[204:205]
	v_pk_fma_f32 v[200:201], v[162:163], v[200:201], v[202:203]
	v_pk_fma_f32 v[202:203], v[178:179], v[122:123], v[182:183]
	v_pk_fma_f32 v[184:185], v[160:161], v[184:185], v[204:205]
	v_pk_fma_f32 v[204:205], v[176:177], v[116:117], v[180:181]
	v_pk_fma_f32 v[176:177], v[176:177], v[112:113], v[180:181]
	v_pk_fma_f32 v[202:203], v[166:167], v[126:127], v[202:203]
	v_pk_fma_f32 v[204:205], v[164:165], v[120:121], v[204:205]
	v_pk_fma_f32 v[164:165], v[164:165], v[116:117], v[176:177]
	v_add_f32_e32 v155, 1.0, v155
	v_pk_fma_f32 v[198:199], v[162:163], v[198:199], v[202:203]
	v_pk_fma_f32 v[202:203], v[178:179], v[118:119], v[182:183]
	v_pk_fma_f32 v[204:205], v[160:161], v[124:125], v[204:205]
	v_pk_fma_f32 v[178:179], v[178:179], v[114:115], v[182:183]
	v_pk_fma_f32 v[214:215], v[160:161], v[120:121], v[164:165]
	v_rcp_f32_e32 v160, v155
	v_add_f32_e32 v155, 1.0, v157
	v_mul_f32_e32 v157, 0xbfb8aa3b, v200
	v_pk_fma_f32 v[202:203], v[166:167], v[122:123], v[202:203]
	v_pk_fma_f32 v[166:167], v[166:167], v[118:119], v[178:179]
	v_exp_f32_e32 v157, v157
	v_mul_f32_e32 v161, 0xbfb8aa3b, v201
	v_pk_fma_f32 v[202:203], v[162:163], v[126:127], v[202:203]
	v_pk_fma_f32 v[212:213], v[162:163], v[122:123], v[166:167]
	v_exp_f32_e32 v163, v161
	v_rcp_f32_e32 v161, v155
	v_add_f32_e32 v155, 1.0, v157
	v_rcp_f32_e32 v162, v155
	v_add_f32_e32 v155, 1.0, v163
	v_rcp_f32_e32 v163, v155
	v_mul_f32_e32 v155, 0xbfb8aa3b, v184
	v_exp_f32_e32 v155, v155
	v_mul_f32_e32 v157, 0xbfb8aa3b, v185
	v_exp_f32_e32 v157, v157
	v_pk_mul_f32 v[216:217], v[196:197], v[160:161]
	v_add_f32_e32 v155, 1.0, v155
	v_rcp_f32_e32 v160, v155
	v_add_f32_e32 v155, 1.0, v157
	v_mul_f32_e32 v157, 0xbfb8aa3b, v198
	v_exp_f32_e32 v157, v157
	v_mul_f32_e32 v161, 0xbfb8aa3b, v199
	v_pk_mul_f32 v[218:219], v[200:201], v[162:163]
	v_exp_f32_e32 v163, v161
	v_rcp_f32_e32 v161, v155
	v_add_f32_e32 v155, 1.0, v157
	v_rcp_f32_e32 v162, v155
	v_add_f32_e32 v155, 1.0, v163
	v_rcp_f32_e32 v163, v155
	v_mul_f32_e32 v155, 0xbfb8aa3b, v204
	v_exp_f32_e32 v155, v155
	v_mul_f32_e32 v157, 0xbfb8aa3b, v205
	v_exp_f32_e32 v157, v157
	v_pk_mul_f32 v[184:185], v[184:185], v[160:161]
	v_add_f32_e32 v155, 1.0, v155
	v_rcp_f32_e32 v160, v155
	v_add_f32_e32 v155, 1.0, v157
	v_mul_f32_e32 v157, 0xbfb8aa3b, v202
	v_exp_f32_e32 v157, v157
	v_mul_f32_e32 v161, 0xbfb8aa3b, v203
	v_exp_f32_e32 v165, v161
	v_rcp_f32_e32 v161, v155
	v_add_f32_e32 v155, 1.0, v157
	v_mul_f32_e32 v157, 0xbfb8aa3b, v214
	v_rcp_f32_e32 v164, v155
	v_add_f32_e32 v155, 1.0, v165
	v_exp_f32_e32 v157, v157
	v_mul_f32_e32 v165, 0xbfb8aa3b, v215
	v_exp_f32_e32 v166, v165
	v_rcp_f32_e32 v165, v155
	v_add_f32_e32 v155, 1.0, v157
	v_mul_f32_e32 v157, 0xbfb8aa3b, v212
	v_rcp_f32_e32 v220, v155
	v_add_f32_e32 v155, 1.0, v166
	v_exp_f32_e32 v157, v157
	v_mul_f32_e32 v166, 0xbfb8aa3b, v213
	v_exp_f32_e32 v166, v166
	v_rcp_f32_e32 v221, v155
	v_add_f32_e32 v155, 1.0, v157
	v_rcp_f32_e32 v222, v155
	v_add_f32_e32 v155, 1.0, v166
	v_rcp_f32_e32 v223, v155
	v_pk_mul_f32 v[224:225], v[198:199], v[162:163]
	v_pk_mul_f32 v[226:227], v[204:205], v[160:161]
	v_pk_mul_f32 v[228:229], v[202:203], v[164:165]
	ds_read_b128 v[196:199], v195 offset:128
	ds_read_b128 v[200:203], v195 offset:384
	ds_read_b128 v[204:207], v195 offset:640
	ds_read_b128 v[208:211], v195 offset:896
	v_pk_mul_f32 v[176:177], v[108:109], v[174:175] op_sel_hi:[1,0]
	v_pk_mul_f32 v[164:165], v[96:97], v[168:169] op_sel_hi:[1,0]
	v_pk_mul_f32 v[180:181], v[100:101], v[170:171] op_sel_hi:[1,0]
	v_pk_mul_f32 v[160:161], v[104:105], v[172:173] op_sel_hi:[1,0]
	v_mov_b32_dpp v96, v164 row_shr:1 row_mask:0xf bank_mask:0xf bound_ctrl:1
	v_mov_b32_dpp v97, v165 row_shr:1 row_mask:0xf bank_mask:0xf bound_ctrl:1
	s_waitcnt lgkmcnt(0)
; #define PG8_LAS __attribute__((address_space(3)))
; __device__ __forceinline__ unsigned pk2(float a, float b) { return pg8::cvt_pk_bf16(a, b); }
; __device__ __forceinline__ float row_up1(float v) { return dpp_mov<0x111>(v); }
;     __device__ __forceinline__ void operator()(f32x4 (&acc)[2][2][4][2], const pg8::Unit& u, int wr, int wc, int fr, int fq) const {
;     ...
;                 {   const PG8_LAS unsigned char* wq = wl + 128 + (8 * fq + 4 * n) * 4;
;                     const f32x4 w0 = *(const PG8_LAS f32x4*)(wq), w1 = *(const PG8_LAS f32x4*)(wq + 256), w2 = *(const PG8_LAS f32x4*)(wq + 512), bb = *(const PG8_LAS f32x4*)(wq + 768);
;                     const f32x4 x0 = acc[ai][1][0][n] * rstd[0], x1 = acc[ai][1][1][n] * rstd[1], x2 = acc[ai][1][2][n] * rstd[2], x3 = acc[ai][1][3][n] * rstd[3];
;                     acc[ai][1][0][n] = x0; acc[ai][1][1][n] = x1; acc[ai][1][2][n] = x2; acc[ai][1][3][n] = x3;
;                     f32x4 p1, p2;
; #pragma unroll
;                     for (int c = 0; c < 4; ++c) { p1[c] = row_up1(x3[c]); p2[c] = row_up1(x2[c]); }
;                     g[0] *= bb + w2 * x0 + w1 * p1 + w0 * p2; g[1] *= bb + w2 * x1 + w1 * x0 + w0 * p1;
;                     g[2] *= bb + w2 * x2 + w1 * x1 + w0 * x0; g[3] *= bb + w2 * x3 + w1 * x2 + w0 * x1;
;                 }
; #pragma unroll
;                 for (int m = 0; m < 4; ++m) { pk[n][m].x = pk2(g[m][0], g[m][1]); pk[n][m].y = pk2(g[m][2], g[m][3]); }
	v_pk_fma_f32 v[108:109], v[176:177], v[204:205], v[208:209]
	v_pk_mul_f32 v[166:167], v[98:99], v[168:169] op_sel_hi:[1,0]
	v_mov_b32_dpp v98, v180 row_shr:1 row_mask:0xf bank_mask:0xf bound_ctrl:1
	v_mov_b32_dpp v99, v181 row_shr:1 row_mask:0xf bank_mask:0xf bound_ctrl:1
	v_pk_fma_f32 v[108:109], v[200:201], v[96:97], v[108:109]
	v_pk_mul_f32 v[178:179], v[110:111], v[174:175] op_sel_hi:[1,0]
	v_pk_fma_f32 v[98:99], v[196:197], v[98:99], v[108:109]
	v_pk_fma_f32 v[108:109], v[160:161], v[204:205], v[208:209]
	v_pk_mul_f32 v[182:183], v[102:103], v[170:171] op_sel_hi:[1,0]
	v_mov_b32_dpp v100, v166 row_shr:1 row_mask:0xf bank_mask:0xf bound_ctrl:1
	v_mov_b32_dpp v101, v167 row_shr:1 row_mask:0xf bank_mask:0xf bound_ctrl:1
	v_pk_fma_f32 v[110:111], v[178:179], v[206:207], v[210:211]
	v_pk_fma_f32 v[108:109], v[176:177], v[200:201], v[108:109]
	v_pk_mul_f32 v[162:163], v[106:107], v[172:173] op_sel_hi:[1,0]
	v_mov_b32_dpp v102, v182 row_shr:1 row_mask:0xf bank_mask:0xf bound_ctrl:1
	v_mov_b32_dpp v103, v183 row_shr:1 row_mask:0xf bank_mask:0xf bound_ctrl:1
	v_pk_fma_f32 v[110:111], v[202:203], v[100:101], v[110:111]
	v_pk_fma_f32 v[96:97], v[196:197], v[96:97], v[108:109]
	v_pk_fma_f32 v[108:109], v[180:181], v[204:205], v[208:209]
	v_pk_fma_f32 v[102:103], v[198:199], v[102:103], v[110:111]
	v_pk_fma_f32 v[110:111], v[162:163], v[206:207], v[210:211]
	v_pk_fma_f32 v[108:109], v[160:161], v[200:201], v[108:109]
	v_pk_fma_f32 v[110:111], v[178:179], v[202:203], v[110:111]
	v_pk_fma_f32 v[108:109], v[176:177], v[196:197], v[108:109]
	v_pk_fma_f32 v[100:101], v[198:199], v[100:101], v[110:111]
	v_pk_mul_f32 v[96:97], v[184:185], v[96:97]
	v_pk_fma_f32 v[110:111], v[182:183], v[206:207], v[210:211]
	v_pk_mul_f32 v[184:185], v[108:109], v[226:227]
	v_pk_fma_f32 v[108:109], v[164:165], v[204:205], v[208:209]
	v_pk_fma_f32 v[204:205], v[166:167], v[206:207], v[210:211]
	v_pk_fma_f32 v[110:111], v[162:163], v[202:203], v[110:111]
	v_pk_fma_f32 v[202:203], v[182:183], v[202:203], v[204:205]
	v_pk_fma_f32 v[108:109], v[180:181], v[200:201], v[108:109]
	v_pk_mul_f32 v[106:107], v[212:213], v[222:223]
	v_pk_fma_f32 v[110:111], v[178:179], v[198:199], v[110:111]
	v_pk_fma_f32 v[108:109], v[160:161], v[196:197], v[108:109]
	v_pk_fma_f32 v[196:197], v[162:163], v[198:199], v[202:203]
	v_pk_mul_f32 v[104:105], v[214:215], v[220:221]
	v_pk_mul_f32 v[102:103], v[218:219], v[102:103]
	v_pk_mul_f32 v[98:99], v[216:217], v[98:99]
	v_pk_mul_f32 v[100:101], v[224:225], v[100:101]
	v_pk_mul_f32 v[110:111], v[110:111], v[228:229]
	v_pk_mul_f32 v[106:107], v[196:197], v[106:107]
	v_pk_mul_f32 v[196:197], v[108:109], v[104:105]
	v_cvt_pk_bf16_f32 v108, v98, v99
	v_cvt_pk_bf16_f32 v109, v102, v103
	v_cvt_pk_bf16_f32 v104, v96, v97
	v_cvt_pk_bf16_f32 v105, v100, v101
	v_cvt_pk_bf16_f32 v100, v184, v185
	v_cvt_pk_bf16_f32 v101, v110, v111
	s_nop 0
	v_cvt_pk_bf16_f32 v96, v196, v197
	v_cvt_pk_bf16_f32 v97, v106, v107
	ds_read_b128 v[196:199], v195 offset:16
	ds_read_b128 v[200:203], v195 offset:272
	ds_read_b128 v[204:207], v195 offset:528
	ds_read_b128 v[208:211], v195 offset:784
	v_pk_mul_f32 v[92:93], v[92:93], v[174:175] op_sel_hi:[1,0]
	v_pk_mul_f32 v[84:85], v[84:85], v[168:169] op_sel_hi:[1,0]
	v_pk_mul_f32 v[88:89], v[88:89], v[170:171] op_sel_hi:[1,0]
	v_pk_mul_f32 v[80:81], v[80:81], v[172:173] op_sel_hi:[1,0]
	v_mov_b32_dpp v98, v84 row_shr:1 row_mask:0xf bank_mask:0xf bound_ctrl:1
	v_mov_b32_dpp v99, v85 row_shr:1 row_mask:0xf bank_mask:0xf bound_ctrl:1
	s_waitcnt lgkmcnt(0)
	v_pk_fma_f32 v[212:213], v[92:93], v[204:205], v[208:209]
	v_mov_b32_dpp v102, v88 row_shr:1 row_mask:0xf bank_mask:0xf bound_ctrl:1
	v_mov_b32_dpp v103, v89 row_shr:1 row_mask:0xf bank_mask:0xf bound_ctrl:1
	v_pk_fma_f32 v[212:213], v[200:201], v[98:99], v[212:213]
	v_pk_mul_f32 v[94:95], v[94:95], v[174:175] op_sel_hi:[1,0]
	v_pk_fma_f32 v[102:103], v[196:197], v[102:103], v[212:213]
	v_pk_mul_f32 v[86:87], v[86:87], v[168:169] op_sel_hi:[1,0]
	v_mul_f32_e32 v155, 0xbfb8aa3b, v102
	v_exp_f32_e32 v155, v155
	v_mul_f32_e32 v157, 0xbfb8aa3b, v103
	v_pk_fma_f32 v[212:213], v[80:81], v[204:205], v[208:209]
	v_exp_f32_e32 v157, v157
	v_pk_mul_f32 v[90:91], v[90:91], v[170:171] op_sel_hi:[1,0]
	v_mov_b32_dpp v106, v86 row_shr:1 row_mask:0xf bank_mask:0xf bound_ctrl:1
	v_mov_b32_dpp v107, v87 row_shr:1 row_mask:0xf bank_mask:0xf bound_ctrl:1
	v_pk_fma_f32 v[184:185], v[94:95], v[206:207], v[210:211]
	v_pk_fma_f32 v[212:213], v[92:93], v[200:201], v[212:213]
	v_mov_b32_dpp v110, v90 row_shr:1 row_mask:0xf bank_mask:0xf bound_ctrl:1
	v_mov_b32_dpp v111, v91 row_shr:1 row_mask:0xf bank_mask:0xf bound_ctrl:1
	v_pk_fma_f32 v[184:185], v[202:203], v[106:107], v[184:185]
	v_pk_fma_f32 v[98:99], v[196:197], v[98:99], v[212:213]
	v_pk_fma_f32 v[212:213], v[88:89], v[204:205], v[208:209]
	v_pk_fma_f32 v[204:205], v[84:85], v[204:205], v[208:209]
	v_pk_fma_f32 v[110:111], v[198:199], v[110:111], v[184:185]
	v_pk_fma_f32 v[212:213], v[80:81], v[200:201], v[212:213]
	v_pk_fma_f32 v[200:201], v[88:89], v[200:201], v[204:205]
	v_add_f32_e32 v155, 1.0, v155
	v_pk_fma_f32 v[212:213], v[92:93], v[196:197], v[212:213]
	v_pk_fma_f32 v[216:217], v[80:81], v[196:197], v[200:201]
	v_rcp_f32_e32 v196, v155
	v_add_f32_e32 v155, 1.0, v157
	v_mul_f32_e32 v157, 0xbfb8aa3b, v110
	v_pk_mul_f32 v[82:83], v[82:83], v[172:173] op_sel_hi:[1,0]
	v_exp_f32_e32 v157, v157
	v_mul_f32_e32 v173, 0xbfb8aa3b, v111
	v_pk_fma_f32 v[184:185], v[82:83], v[206:207], v[210:211]
	v_exp_f32_e32 v173, v173
	v_pk_fma_f32 v[184:185], v[94:95], v[202:203], v[184:185]
	v_rcp_f32_e32 v197, v155
	v_pk_fma_f32 v[106:107], v[198:199], v[106:107], v[184:185]
; #define PG8_LAS __attribute__((address_space(3)))
; __device__ __forceinline__ unsigned pk2(float a, float b) { return pg8::cvt_pk_bf16(a, b); }
; __device__ __forceinline__ float row_up1(float v) { return dpp_mov<0x111>(v); }
; __device__ __forceinline__ float siluf_(float x) { return x * __builtin_amdgcn_rcpf(1.0f + __builtin_amdgcn_exp2f(x * -1.4426950408889634f)); }
;     __device__ __forceinline__ void operator()(f32x4 (&acc)[2][2][4][2], const pg8::Unit& u, int wr, int wc, int fr, int fq) const {
;     ...
;                     g[0] = bb + w2 * x0 + w1 * p1 + w0 * p2; g[1] = bb + w2 * x1 + w1 * x0 + w0 * p1;
;                     g[2] = bb + w2 * x2 + w1 * x1 + w0 * x0; g[3] = bb + w2 * x3 + w1 * x2 + w0 * x1;
; #pragma unroll
;                     for (int m = 0; m < 4; ++m)
; #pragma unroll
;                         for (int c = 0; c < 4; ++c) g[m][c] = siluf_(g[m][c]);
;                 }
;                 __builtin_amdgcn_sched_barrier(0);
;                 {   const PG8_LAS unsigned char* wq = wl + 128 + (8 * fq + 4 * n) * 4;
;                     const f32x4 w0 = *(const PG8_LAS f32x4*)(wq), w1 = *(const PG8_LAS f32x4*)(wq + 256), w2 = *(const PG8_LAS f32x4*)(wq + 512), bb = *(const PG8_LAS f32x4*)(wq + 768);
;                     const f32x4 x0 = acc[ai][1][0][n] * rstd[0], x1 = acc[ai][1][1][n] * rstd[1], x2 = acc[ai][1][2][n] * rstd[2], x3 = acc[ai][1][3][n] * rstd[3];
;                     acc[ai][1][0][n] = x0; acc[ai][1][1][n] = x1; acc[ai][1][2][n] = x2; acc[ai][1][3][n] = x3;
;                     f32x4 p1, p2;
; #pragma unroll
;                     for (int c = 0; c < 4; ++c) { p1[c] = row_up1(x3[c]); p2[c] = row_up1(x2[c]); }
;                     g[0] *= bb + w2 * x0 + w1 * p1 + w0 * p2; g[1] *= bb + w2 * x1 + w1 * x0 + w0 * p1;
;                     g[2] *= bb + w2 * x2 + w1 * x1 + w0 * x0; g[3] *= bb + w2 * x3 + w1 * x2 + w0 * x1;
;                 }
; #pragma unroll
;                 for (int m = 0; m < 4; ++m) { pk[n][m].x = pk2(g[m][0], g[m][1]); pk[n][m].y = pk2(g[m][2], g[m][3]); }
;                 __builtin_amdgcn_sched_barrier(0);
;             }
; #pragma unroll
;             for (int m = 0; m < 4; ++m) if (fr != 0 || m >= 2) {
;                 u32x4 w; w.x = pk[0][m].x; w.y = pk[0][m].y; w.z = pk[1][m].x; w.w = pk[1][m].y;
;                 *(u32x4*)(ACT + (size_t)(tb + m) * DFF + colj) = w; }
	v_pk_fma_f32 v[184:185], v[90:91], v[206:207], v[210:211]
	v_pk_fma_f32 v[206:207], v[86:87], v[206:207], v[210:211]
	v_pk_fma_f32 v[184:185], v[82:83], v[202:203], v[184:185]
	v_pk_fma_f32 v[202:203], v[90:91], v[202:203], v[206:207]
	v_add_f32_e32 v155, 1.0, v157
	v_pk_fma_f32 v[184:185], v[94:95], v[198:199], v[184:185]
	v_pk_fma_f32 v[214:215], v[82:83], v[198:199], v[202:203]
	v_rcp_f32_e32 v198, v155
	v_add_f32_e32 v155, 1.0, v173
	v_rcp_f32_e32 v199, v155
	v_mul_f32_e32 v155, 0xbfb8aa3b, v98
	v_exp_f32_e32 v155, v155
	v_mul_f32_e32 v157, 0xbfb8aa3b, v99
	v_exp_f32_e32 v157, v157
	v_pk_mul_f32 v[102:103], v[102:103], v[196:197]
	v_add_f32_e32 v155, 1.0, v155
	v_rcp_f32_e32 v196, v155
	v_add_f32_e32 v155, 1.0, v157
	v_mul_f32_e32 v157, 0xbfb8aa3b, v106
	v_exp_f32_e32 v157, v157
	v_mul_f32_e32 v173, 0xbfb8aa3b, v107
	v_exp_f32_e32 v173, v173
	v_rcp_f32_e32 v197, v155
	v_add_f32_e32 v155, 1.0, v157
	v_pk_mul_f32 v[110:111], v[110:111], v[198:199]
	v_rcp_f32_e32 v198, v155
	v_add_f32_e32 v155, 1.0, v173
	v_rcp_f32_e32 v199, v155
	v_mul_f32_e32 v155, 0xbfb8aa3b, v212
	v_exp_f32_e32 v155, v155
	v_mul_f32_e32 v157, 0xbfb8aa3b, v213
	v_exp_f32_e32 v157, v157
	v_pk_mul_f32 v[98:99], v[98:99], v[196:197]
	v_add_f32_e32 v155, 1.0, v155
	v_rcp_f32_e32 v196, v155
	v_add_f32_e32 v155, 1.0, v157
	v_mul_f32_e32 v157, 0xbfb8aa3b, v184
	v_exp_f32_e32 v157, v157
	v_mul_f32_e32 v173, 0xbfb8aa3b, v185
	v_exp_f32_e32 v173, v173
	v_rcp_f32_e32 v197, v155
	v_add_f32_e32 v155, 1.0, v157
	v_mul_f32_e32 v157, 0xbfb8aa3b, v216
	v_rcp_f32_e32 v200, v155
	v_add_f32_e32 v155, 1.0, v173
	v_exp_f32_e32 v157, v157
	v_mul_f32_e32 v173, 0xbfb8aa3b, v217
	v_exp_f32_e32 v173, v173
	v_rcp_f32_e32 v201, v155
	v_add_f32_e32 v155, 1.0, v157
	v_mul_f32_e32 v157, 0xbfb8aa3b, v214
	v_rcp_f32_e32 v218, v155
	v_add_f32_e32 v155, 1.0, v173
	v_exp_f32_e32 v157, v157
	v_mul_f32_e32 v173, 0xbfb8aa3b, v215
	v_exp_f32_e32 v173, v173
	v_rcp_f32_e32 v219, v155
	v_add_f32_e32 v155, 1.0, v157
	v_rcp_f32_e32 v220, v155
	v_add_f32_e32 v155, 1.0, v173
	v_pk_mul_f32 v[106:107], v[106:107], v[198:199]
	v_rcp_f32_e32 v221, v155
	v_pk_mul_f32 v[212:213], v[212:213], v[196:197]
	v_pk_mul_f32 v[222:223], v[184:185], v[200:201]
	ds_read_b128 v[196:199], v195 offset:144
	ds_read_b128 v[200:203], v195 offset:400
	ds_read_b128 v[204:207], v195 offset:656
	ds_read_b128 v[208:211], v195 offset:912
	v_pk_mul_f32 v[184:185], v[66:67], v[174:175] op_sel_hi:[1,0]
	v_pk_mul_f32 v[174:175], v[64:65], v[174:175] op_sel_hi:[1,0]
	v_pk_mul_f32 v[66:67], v[68:69], v[172:173] op_sel_hi:[1,0]
	v_pk_mul_f32 v[68:69], v[76:77], v[168:169] op_sel_hi:[1,0]
	v_pk_mul_f32 v[70:71], v[70:71], v[172:173] op_sel_hi:[1,0]
	v_pk_mul_f32 v[172:173], v[74:75], v[170:171] op_sel_hi:[1,0]
	v_pk_mul_f32 v[74:75], v[72:73], v[170:171] op_sel_hi:[1,0]
	v_mov_b32_dpp v64, v68 row_shr:1 row_mask:0xf bank_mask:0xf bound_ctrl:1
	v_mov_b32_dpp v65, v69 row_shr:1 row_mask:0xf bank_mask:0xf bound_ctrl:1
	v_pk_mul_f32 v[216:217], v[216:217], v[218:219]
	s_waitcnt lgkmcnt(0)
	v_pk_fma_f32 v[218:219], v[174:175], v[204:205], v[208:209]
	v_pk_mul_f32 v[72:73], v[78:79], v[168:169] op_sel_hi:[1,0]
	v_mov_b32_dpp v76, v74 row_shr:1 row_mask:0xf bank_mask:0xf bound_ctrl:1
	v_mov_b32_dpp v77, v75 row_shr:1 row_mask:0xf bank_mask:0xf bound_ctrl:1
	v_pk_fma_f32 v[218:219], v[200:201], v[64:65], v[218:219]
	v_mov_b32_dpp v78, v72 row_shr:1 row_mask:0xf bank_mask:0xf bound_ctrl:1
	v_mov_b32_dpp v79, v73 row_shr:1 row_mask:0xf bank_mask:0xf bound_ctrl:1
	v_pk_mul_f32 v[214:215], v[214:215], v[220:221]
	v_pk_fma_f32 v[220:221], v[184:185], v[206:207], v[210:211]
	v_pk_fma_f32 v[76:77], v[196:197], v[76:77], v[218:219]
	v_mov_b32_dpp v224, v172 row_shr:1 row_mask:0xf bank_mask:0xf bound_ctrl:1
	v_mov_b32_dpp v225, v173 row_shr:1 row_mask:0xf bank_mask:0xf bound_ctrl:1
	v_pk_fma_f32 v[220:221], v[202:203], v[78:79], v[220:221]
	v_pk_mul_f32 v[76:77], v[102:103], v[76:77]
	v_pk_fma_f32 v[102:103], v[66:67], v[204:205], v[208:209]
	v_pk_fma_f32 v[218:219], v[198:199], v[224:225], v[220:221]
	v_pk_fma_f32 v[102:103], v[174:175], v[200:201], v[102:103]
	v_pk_mul_f32 v[218:219], v[110:111], v[218:219]
	v_pk_fma_f32 v[110:111], v[70:71], v[206:207], v[210:211]
	v_pk_fma_f32 v[64:65], v[196:197], v[64:65], v[102:103]
	v_pk_fma_f32 v[102:103], v[172:173], v[206:207], v[210:211]
	v_pk_fma_f32 v[110:111], v[184:185], v[202:203], v[110:111]
	v_pk_fma_f32 v[102:103], v[70:71], v[202:203], v[102:103]
	v_pk_fma_f32 v[78:79], v[198:199], v[78:79], v[110:111]
	v_pk_mul_f32 v[64:65], v[98:99], v[64:65]
	v_pk_fma_f32 v[98:99], v[74:75], v[204:205], v[208:209]
	v_pk_fma_f32 v[102:103], v[184:185], v[198:199], v[102:103]
	v_pk_mul_f32 v[78:79], v[106:107], v[78:79]
	v_pk_fma_f32 v[98:99], v[66:67], v[200:201], v[98:99]
	v_pk_mul_f32 v[220:221], v[222:223], v[102:103]
	v_pk_fma_f32 v[102:103], v[68:69], v[204:205], v[208:209]
	v_pk_fma_f32 v[106:107], v[72:73], v[206:207], v[210:211]
	v_pk_fma_f32 v[98:99], v[174:175], v[196:197], v[98:99]
	v_pk_fma_f32 v[106:107], v[172:173], v[202:203], v[106:107]
	v_pk_fma_f32 v[102:103], v[74:75], v[200:201], v[102:103]
	v_pk_mul_f32 v[98:99], v[212:213], v[98:99]
	v_pk_fma_f32 v[102:103], v[66:67], v[196:197], v[102:103]
	v_pk_fma_f32 v[106:107], v[70:71], v[198:199], v[106:107]
	v_pk_mul_f32 v[198:199], v[216:217], v[102:103]
	v_pk_mul_f32 v[196:197], v[214:215], v[106:107]
	v_cvt_pk_bf16_f32 v110, v76, v77
	v_cvt_pk_bf16_f32 v111, v218, v219
	v_cvt_pk_bf16_f32 v106, v64, v65
	v_cvt_pk_bf16_f32 v107, v78, v79
	v_cvt_pk_bf16_f32 v102, v98, v99
	v_cvt_pk_bf16_f32 v103, v220, v221
	v_cvt_pk_bf16_f32 v98, v198, v199
	s_nop 0
	v_cvt_pk_bf16_f32 v99, v196, v197
	v_lshlrev_b64 v[64:65], 1, v[158:159]
	s_and_saveexec_b64 s[8:9], s[0:1]
	s_cbranch_execz .LBB0_750
	v_mov_b64_e32 v[76:77], s[22:23]
	v_mad_i64_i32 v[78:79], s[10:11], v148, s56, v[76:77]
	v_mad_i64_i32 v[76:77], s[10:11], v150, s56, v[76:77]
	v_lshl_add_u64 v[78:79], v[78:79], 0, v[64:65]
	v_lshl_add_u64 v[76:77], v[76:77], 0, v[64:65]
	global_store_dwordx4 v[78:79], v[108:111], off
	global_store_dwordx4 v[76:77], v[104:107], off

; #define PG8_LAS __attribute__((address_space(3)))
; __device__ __forceinline__ float row_up1(float v) { return dpp_mov<0x111>(v); }
; __device__ __forceinline__ float siluf_(float x) { return x * __builtin_amdgcn_rcpf(1.0f + __builtin_amdgcn_exp2f(x * -1.4426950408889634f)); }
;     __device__ __forceinline__ void operator()(f32x4 (&acc)[2][2][4][2], const pg8::Unit& u, int wr, int wc, int fr, int fq) const {
;     ...
;         for (int ai = 0; ai < 2; ++ai) {
;             const int tb = u.pm * 256 + ai * 128 + wr * 64 + 4 * fr;
;             float rstd[4];
; #pragma unroll
;             for (int m = 0; m < 4; ++m) { const f32x4 sv = *(const f32x4*)(SS + (size_t)(tb + m) * 16 + 4 * fq); float s = (sv[0] + sv[1]) + (sv[2] + sv[3]); s += __shfl_xor(s, 16); s += __shfl_xor(s, 32);
;                 rstd[m] = rsqrtf(s * (1.0f / 1024.0f) + EPS); }
;             u32x2 pk[2][4];
; #pragma unroll
;             for (int n = 0; n < 2; ++n) {
;                 f32x4 g[4];
;                 {   const PG8_LAS unsigned char* wq = wl + (8 * fq + 4 * n) * 4;
;                     const f32x4 w0 = *(const PG8_LAS f32x4*)(wq), w1 = *(const PG8_LAS f32x4*)(wq + 256), w2 = *(const PG8_LAS f32x4*)(wq + 512), bb = *(const PG8_LAS f32x4*)(wq + 768);
;                     const f32x4 x0 = acc[ai][0][0][n] * rstd[0], x1 = acc[ai][0][1][n] * rstd[1], x2 = acc[ai][0][2][n] * rstd[2], x3 = acc[ai][0][3][n] * rstd[3];
;                     acc[ai][0][0][n] = x0; acc[ai][0][1][n] = x1; acc[ai][0][2][n] = x2; acc[ai][0][3][n] = x3;
;                     f32x4 p1, p2;
; #pragma unroll
;                     for (int c = 0; c < 4; ++c) { p1[c] = row_up1(x3[c]); p2[c] = row_up1(x2[c]); }
;                     g[0] = bb + w2 * x0 + w1 * p1 + w0 * p2; g[1] = bb + w2 * x1 + w1 * x0 + w0 * p1;
;                     g[2] = bb + w2 * x2 + w1 * x1 + w0 * x0; g[3] = bb + w2 * x3 + w1 * x2 + w0 * x1;
; #pragma unroll
;                     for (int m = 0; m < 4; ++m)
; #pragma unroll
;                         for (int c = 0; c < 4; ++c) g[m][c] = siluf_(g[m][c]);
.LBB0_754:
	s_or_b64 exec, exec, s[8:9]
	s_nop 0
	v_add_u32_e32 v66, 0x80, v148
	v_ashrrev_i32_e32 v67, 31, v66
	v_add_u32_e32 v68, 0x81, v148
	v_ashrrev_i32_e32 v69, 31, v68
	v_add_u32_e32 v70, 0x82, v148
	v_ashrrev_i32_e32 v71, 31, v70
	v_add_u32_e32 v72, 0x83, v148
	v_ashrrev_i32_e32 v73, 31, v72
	s_waitcnt vmcnt(8)
	v_mov_b32_e32 v74, v230
	v_mov_b32_e32 v75, v231
	v_mov_b32_e32 v76, v232
	v_mov_b32_e32 v77, v233
	v_mov_b32_e32 v78, v234
	v_mov_b32_e32 v79, v235
	v_mov_b32_e32 v80, v236
	v_mov_b32_e32 v81, v237
	v_mov_b32_e32 v82, v238
	v_mov_b32_e32 v83, v239
	v_mov_b32_e32 v84, v240
	v_mov_b32_e32 v85, v241
	v_mov_b32_e32 v86, v242
	v_mov_b32_e32 v87, v243
	v_mov_b32_e32 v88, v244
	v_mov_b32_e32 v89, v245
	v_mov_b32_e32 v90, v75
	v_mov_b32_e32 v91, v76
	v_mov_b32_e32 v75, v77
	v_mov_b32_e32 v76, v79
	v_mov_b32_e32 v77, v80
	v_mov_b32_e32 v79, v81
	v_mov_b32_e32 v80, v83
	v_mov_b32_e32 v81, v84
	v_mov_b32_e32 v83, v85
	v_pk_add_f32 v[74:75], v[90:91], v[74:75]
	v_pk_add_f32 v[76:77], v[76:77], v[78:79]
	v_mov_b32_e32 v84, v87
	v_mov_b32_e32 v85, v88
	v_mov_b32_e32 v87, v89
	v_pk_add_f32 v[78:79], v[80:81], v[82:83]
	v_pk_add_f32 v[80:81], v[84:85], v[86:87]
	v_mov_b32_e32 v82, v76
	v_mov_b32_e32 v83, v74
	v_mov_b32_e32 v74, v77
	v_mov_b32_e32 v76, v80
	v_mov_b32_e32 v77, v78
	v_mov_b32_e32 v78, v81
	v_pk_add_f32 v[74:75], v[82:83], v[74:75]
	v_pk_add_f32 v[76:77], v[76:77], v[78:79]
	ds_bpermute_b32 v79, v149, v75
	ds_bpermute_b32 v78, v149, v74
	ds_bpermute_b32 v81, v149, v77
	ds_bpermute_b32 v80, v149, v76
	v_mov_b64_e32 v[82:83], s[38:39]
	s_waitcnt lgkmcnt(2)
	v_pk_add_f32 v[84:85], v[74:75], v[78:79]
	ds_bpermute_b32 v89, v151, v85
	s_waitcnt lgkmcnt(1)
	v_pk_add_f32 v[86:87], v[76:77], v[80:81]
	ds_bpermute_b32 v88, v151, v84
	ds_bpermute_b32 v99, v151, v87
	ds_bpermute_b32 v98, v151, v86
	ds_read_b128 v[74:77], v195
	ds_read_b128 v[78:81], v195 offset:256
	ds_read_b128 v[90:93], v195 offset:512
	ds_read_b128 v[94:97], v195 offset:768
	s_waitcnt lgkmcnt(6)
	v_pk_add_f32 v[84:85], v[84:85], v[88:89]
	s_nop 0
	v_pk_fma_f32 v[84:85], v[84:85], s[24:25], v[82:83] op_sel_hi:[1,0,0]
	s_waitcnt lgkmcnt(4)
	v_pk_add_f32 v[86:87], v[86:87], v[98:99]
	v_mul_f32_e32 v67, 0x4b800000, v85
	v_pk_fma_f32 v[82:83], v[86:87], s[24:25], v[82:83] op_sel_hi:[1,0,0]
	v_cmp_gt_f32_e32 vcc, s63, v85
	v_mul_f32_e32 v73, 0x4b800000, v82
	v_cmp_gt_f32_e64 s[12:13], s63, v82
	v_mul_f32_e32 v69, 0x4b800000, v84
	v_mul_f32_e32 v71, 0x4b800000, v83
	v_cndmask_b32_e32 v67, v85, v67, vcc
	v_cmp_gt_f32_e64 s[8:9], s63, v84
	v_cmp_gt_f32_e64 s[10:11], s63, v83
	v_cndmask_b32_e64 v73, v82, v73, s[12:13]
	v_cndmask_b32_e64 v69, v84, v69, s[8:9]
	v_cndmask_b32_e64 v71, v83, v71, s[10:11]
	v_rsq_f32_e32 v67, v67
	v_rsq_f32_e32 v73, v73
	v_rsq_f32_e32 v69, v69
	v_rsq_f32_e32 v71, v71
	v_mul_f32_e32 v82, 0x45800000, v67
	v_mul_f32_e32 v85, 0x45800000, v73
	v_mul_f32_e32 v83, 0x45800000, v69
	v_mul_f32_e32 v84, 0x45800000, v71
	v_cndmask_b32_e32 v88, v67, v82, vcc
	v_cndmask_b32_e64 v82, v73, v85, s[12:13]
	v_cndmask_b32_e64 v84, v71, v84, s[10:11]
	v_pk_mul_f32 v[60:61], v[60:61], v[88:89] op_sel_hi:[1,0]
	v_pk_mul_f32 v[48:49], v[48:49], v[82:83] op_sel_hi:[1,0]
	v_pk_mul_f32 v[52:53], v[52:53], v[84:85] op_sel_hi:[1,0]
	s_waitcnt lgkmcnt(0)
	v_pk_fma_f32 v[108:109], v[90:91], v[60:61], v[94:95]
	v_mov_b32_dpp v98, v48 row_shr:1 row_mask:0xf bank_mask:0xf bound_ctrl:1
	v_mov_b32_dpp v99, v49 row_shr:1 row_mask:0xf bank_mask:0xf bound_ctrl:1
	v_mov_b32_dpp v100, v52 row_shr:1 row_mask:0xf bank_mask:0xf bound_ctrl:1
	v_mov_b32_dpp v101, v53 row_shr:1 row_mask:0xf bank_mask:0xf bound_ctrl:1
	v_pk_fma_f32 v[108:109], v[78:79], v[98:99], v[108:109]
	v_cndmask_b32_e64 v86, v69, v83, s[8:9]
	v_pk_fma_f32 v[100:101], v[74:75], v[100:101], v[108:109]
	v_pk_mul_f32 v[62:63], v[62:63], v[88:89] op_sel_hi:[1,0]
	v_mul_f32_e32 v67, 0xbfb8aa3b, v100
	v_exp_f32_e32 v67, v67
	v_mul_f32_e32 v69, 0xbfb8aa3b, v101
	v_pk_mul_f32 v[50:51], v[50:51], v[82:83] op_sel_hi:[1,0]
	v_exp_f32_e32 v69, v69
	v_pk_mul_f32 v[56:57], v[56:57], v[86:87] op_sel_hi:[1,0]
	v_pk_mul_f32 v[54:55], v[54:55], v[84:85] op_sel_hi:[1,0]
	v_mov_b32_dpp v102, v50 row_shr:1 row_mask:0xf bank_mask:0xf bound_ctrl:1
	v_mov_b32_dpp v103, v51 row_shr:1 row_mask:0xf bank_mask:0xf bound_ctrl:1
	v_pk_fma_f32 v[106:107], v[92:93], v[62:63], v[96:97]
	v_mov_b32_dpp v104, v54 row_shr:1 row_mask:0xf bank_mask:0xf bound_ctrl:1
	v_mov_b32_dpp v105, v55 row_shr:1 row_mask:0xf bank_mask:0xf bound_ctrl:1
	v_pk_fma_f32 v[112:113], v[90:91], v[56:57], v[94:95]
	v_pk_fma_f32 v[106:107], v[80:81], v[102:103], v[106:107]
	v_pk_fma_f32 v[108:109], v[90:91], v[52:53], v[94:95]
	v_pk_fma_f32 v[90:91], v[90:91], v[48:49], v[94:95]
	v_pk_fma_f32 v[112:113], v[78:79], v[60:61], v[112:113]
	v_pk_fma_f32 v[104:105], v[76:77], v[104:105], v[106:107]
	v_pk_fma_f32 v[108:109], v[78:79], v[56:57], v[108:109]
	v_pk_fma_f32 v[78:79], v[78:79], v[52:53], v[90:91]
	v_add_f32_e32 v67, 1.0, v67
	v_pk_fma_f32 v[98:99], v[74:75], v[98:99], v[112:113]
	v_pk_fma_f32 v[108:109], v[74:75], v[60:61], v[108:109]
	v_pk_fma_f32 v[116:117], v[74:75], v[56:57], v[78:79]
	v_rcp_f32_e32 v74, v67
	v_add_f32_e32 v67, 1.0, v69
	v_mul_f32_e32 v69, 0xbfb8aa3b, v104
	v_exp_f32_e32 v69, v69
	v_mul_f32_e32 v71, 0xbfb8aa3b, v105
	v_exp_f32_e32 v71, v71
	v_pk_mul_f32 v[58:59], v[58:59], v[86:87] op_sel_hi:[1,0]
	v_pk_fma_f32 v[106:107], v[92:93], v[54:55], v[96:97]
	v_pk_fma_f32 v[110:111], v[92:93], v[58:59], v[96:97]
	v_pk_fma_f32 v[92:93], v[92:93], v[50:51], v[96:97]
	v_pk_fma_f32 v[110:111], v[80:81], v[62:63], v[110:111]
	v_pk_fma_f32 v[106:107], v[80:81], v[58:59], v[106:107]
; #define PG8_LAS __attribute__((address_space(3)))
; __device__ __forceinline__ unsigned pk2(float a, float b) { return pg8::cvt_pk_bf16(a, b); }
; __device__ __forceinline__ float row_up1(float v) { return dpp_mov<0x111>(v); }
;     __device__ __forceinline__ void operator()(f32x4 (&acc)[2][2][4][2], const pg8::Unit& u, int wr, int wc, int fr, int fq) const {
;     ...
;                 {   const PG8_LAS unsigned char* wq = wl + 128 + (8 * fq + 4 * n) * 4;
;                     const f32x4 w0 = *(const PG8_LAS f32x4*)(wq), w1 = *(const PG8_LAS f32x4*)(wq + 256), w2 = *(const PG8_LAS f32x4*)(wq + 512), bb = *(const PG8_LAS f32x4*)(wq + 768);
;                     const f32x4 x0 = acc[ai][1][0][n] * rstd[0], x1 = acc[ai][1][1][n] * rstd[1], x2 = acc[ai][1][2][n] * rstd[2], x3 = acc[ai][1][3][n] * rstd[3];
;                     acc[ai][1][0][n] = x0; acc[ai][1][1][n] = x1; acc[ai][1][2][n] = x2; acc[ai][1][3][n] = x3;
;                     f32x4 p1, p2;
; #pragma unroll
;                     for (int c = 0; c < 4; ++c) { p1[c] = row_up1(x3[c]); p2[c] = row_up1(x2[c]); }
;                     g[0] *= bb + w2 * x0 + w1 * p1 + w0 * p2; g[1] *= bb + w2 * x1 + w1 * x0 + w0 * p1;
;                     g[2] *= bb + w2 * x2 + w1 * x1 + w0 * x0; g[3] *= bb + w2 * x3 + w1 * x2 + w0 * x1;
;                 }
; #pragma unroll
;                 for (int m = 0; m < 4; ++m) { pk[n][m].x = pk2(g[m][0], g[m][1]); pk[n][m].y = pk2(g[m][2], g[m][3]); }
	v_pk_fma_f32 v[80:81], v[80:81], v[54:55], v[92:93]
	v_rcp_f32_e32 v75, v67
	v_add_f32_e32 v67, 1.0, v69
	v_pk_fma_f32 v[102:103], v[76:77], v[102:103], v[110:111]
	v_pk_fma_f32 v[106:107], v[76:77], v[62:63], v[106:107]
	v_pk_fma_f32 v[114:115], v[76:77], v[58:59], v[80:81]
	v_rcp_f32_e32 v76, v67
	v_add_f32_e32 v67, 1.0, v71
	v_rcp_f32_e32 v77, v67
	v_mul_f32_e32 v67, 0xbfb8aa3b, v98
	v_exp_f32_e32 v67, v67
	v_mul_f32_e32 v69, 0xbfb8aa3b, v99
	v_exp_f32_e32 v69, v69
	v_pk_mul_f32 v[118:119], v[100:101], v[74:75]
	v_add_f32_e32 v67, 1.0, v67
	v_rcp_f32_e32 v74, v67
	v_add_f32_e32 v67, 1.0, v69
	v_mul_f32_e32 v69, 0xbfb8aa3b, v102
	v_exp_f32_e32 v69, v69
	v_mul_f32_e32 v71, 0xbfb8aa3b, v103
	v_exp_f32_e32 v71, v71
	v_rcp_f32_e32 v75, v67
	v_add_f32_e32 v67, 1.0, v69
	v_pk_mul_f32 v[120:121], v[104:105], v[76:77]
	v_rcp_f32_e32 v76, v67
	v_add_f32_e32 v67, 1.0, v71
	v_rcp_f32_e32 v77, v67
	v_mul_f32_e32 v67, 0xbfb8aa3b, v108
	v_exp_f32_e32 v67, v67
	v_mul_f32_e32 v69, 0xbfb8aa3b, v109
	v_exp_f32_e32 v69, v69
	v_pk_mul_f32 v[122:123], v[98:99], v[74:75]
	v_add_f32_e32 v67, 1.0, v67
	v_rcp_f32_e32 v74, v67
	v_add_f32_e32 v67, 1.0, v69
	v_mul_f32_e32 v69, 0xbfb8aa3b, v106
	v_exp_f32_e32 v69, v69
	v_mul_f32_e32 v71, 0xbfb8aa3b, v107
	v_exp_f32_e32 v71, v71
	v_rcp_f32_e32 v75, v67
	v_add_f32_e32 v67, 1.0, v69
	v_mul_f32_e32 v69, 0xbfb8aa3b, v116
	v_rcp_f32_e32 v78, v67
	v_add_f32_e32 v67, 1.0, v71
	v_exp_f32_e32 v69, v69
	v_mul_f32_e32 v71, 0xbfb8aa3b, v117
	v_exp_f32_e32 v71, v71
	v_rcp_f32_e32 v79, v67
	v_add_f32_e32 v67, 1.0, v69
	v_mul_f32_e32 v69, 0xbfb8aa3b, v114
	v_rcp_f32_e32 v124, v67
	v_add_f32_e32 v67, 1.0, v71
	v_exp_f32_e32 v69, v69
	v_mul_f32_e32 v71, 0xbfb8aa3b, v115
	v_exp_f32_e32 v71, v71
	v_rcp_f32_e32 v125, v67
	v_add_f32_e32 v67, 1.0, v69
	v_rcp_f32_e32 v126, v67
	v_add_f32_e32 v67, 1.0, v71
	v_rcp_f32_e32 v127, v67
	v_pk_mul_f32 v[148:149], v[102:103], v[76:77]
	v_pk_mul_f32 v[150:151], v[108:109], v[74:75]
	v_pk_mul_f32 v[154:155], v[106:107], v[78:79]
	ds_read_b128 v[98:101], v195 offset:128
	ds_read_b128 v[102:105], v195 offset:384
	ds_read_b128 v[106:109], v195 offset:640
	ds_read_b128 v[110:113], v195 offset:896
	v_pk_mul_f32 v[90:91], v[44:45], v[88:89] op_sel_hi:[1,0]
	v_pk_mul_f32 v[78:79], v[32:33], v[82:83] op_sel_hi:[1,0]
	v_pk_mul_f32 v[94:95], v[36:37], v[84:85] op_sel_hi:[1,0]
	v_pk_mul_f32 v[74:75], v[40:41], v[86:87] op_sel_hi:[1,0]
	v_mov_b32_dpp v32, v78 row_shr:1 row_mask:0xf bank_mask:0xf bound_ctrl:1
	v_mov_b32_dpp v33, v79 row_shr:1 row_mask:0xf bank_mask:0xf bound_ctrl:1
	s_waitcnt lgkmcnt(0)
	v_pk_fma_f32 v[44:45], v[90:91], v[106:107], v[110:111]
	v_pk_mul_f32 v[80:81], v[34:35], v[82:83] op_sel_hi:[1,0]
	v_mov_b32_dpp v34, v94 row_shr:1 row_mask:0xf bank_mask:0xf bound_ctrl:1
	v_mov_b32_dpp v35, v95 row_shr:1 row_mask:0xf bank_mask:0xf bound_ctrl:1
	v_pk_fma_f32 v[44:45], v[102:103], v[32:33], v[44:45]
	v_pk_mul_f32 v[92:93], v[46:47], v[88:89] op_sel_hi:[1,0]
	v_pk_fma_f32 v[34:35], v[98:99], v[34:35], v[44:45]
	v_pk_fma_f32 v[44:45], v[74:75], v[106:107], v[110:111]
	v_pk_mul_f32 v[96:97], v[38:39], v[84:85] op_sel_hi:[1,0]
	v_mov_b32_dpp v36, v80 row_shr:1 row_mask:0xf bank_mask:0xf bound_ctrl:1
	v_mov_b32_dpp v37, v81 row_shr:1 row_mask:0xf bank_mask:0xf bound_ctrl:1
	v_pk_fma_f32 v[46:47], v[92:93], v[108:109], v[112:113]
	v_pk_fma_f32 v[44:45], v[90:91], v[102:103], v[44:45]
	v_pk_mul_f32 v[76:77], v[42:43], v[86:87] op_sel_hi:[1,0]
	v_mov_b32_dpp v38, v96 row_shr:1 row_mask:0xf bank_mask:0xf bound_ctrl:1
	v_mov_b32_dpp v39, v97 row_shr:1 row_mask:0xf bank_mask:0xf bound_ctrl:1
	v_pk_fma_f32 v[46:47], v[104:105], v[36:37], v[46:47]
	v_pk_fma_f32 v[32:33], v[98:99], v[32:33], v[44:45]
	v_pk_fma_f32 v[44:45], v[94:95], v[106:107], v[110:111]
	v_pk_fma_f32 v[38:39], v[100:101], v[38:39], v[46:47]
	v_pk_fma_f32 v[46:47], v[76:77], v[108:109], v[112:113]
	v_pk_fma_f32 v[44:45], v[74:75], v[102:103], v[44:45]
	v_pk_fma_f32 v[46:47], v[92:93], v[104:105], v[46:47]
	v_pk_fma_f32 v[44:45], v[90:91], v[98:99], v[44:45]
	v_pk_mul_f32 v[42:43], v[114:115], v[126:127]
	v_pk_fma_f32 v[36:37], v[100:101], v[36:37], v[46:47]
	v_pk_fma_f32 v[46:47], v[96:97], v[108:109], v[112:113]
	v_pk_mul_f32 v[114:115], v[44:45], v[150:151]
	v_pk_fma_f32 v[44:45], v[78:79], v[106:107], v[110:111]
	v_pk_fma_f32 v[106:107], v[80:81], v[108:109], v[112:113]
	v_pk_fma_f32 v[46:47], v[76:77], v[104:105], v[46:47]
	v_pk_fma_f32 v[104:105], v[96:97], v[104:105], v[106:107]
	v_pk_fma_f32 v[44:45], v[94:95], v[102:103], v[44:45]
	v_pk_mul_f32 v[40:41], v[116:117], v[124:125]
	v_pk_fma_f32 v[46:47], v[92:93], v[100:101], v[46:47]
	v_pk_fma_f32 v[44:45], v[74:75], v[98:99], v[44:45]
	v_pk_fma_f32 v[98:99], v[76:77], v[100:101], v[104:105]
	v_pk_mul_f32 v[38:39], v[120:121], v[38:39]
	v_pk_mul_f32 v[34:35], v[118:119], v[34:35]
	v_pk_mul_f32 v[36:37], v[148:149], v[36:37]
	v_pk_mul_f32 v[32:33], v[122:123], v[32:33]
	v_pk_mul_f32 v[46:47], v[46:47], v[154:155]
	v_pk_mul_f32 v[42:43], v[98:99], v[42:43]
	v_pk_mul_f32 v[98:99], v[44:45], v[40:41]
	v_cvt_pk_bf16_f32 v44, v34, v35
	v_cvt_pk_bf16_f32 v45, v38, v39
	v_cvt_pk_bf16_f32 v40, v32, v33
	v_cvt_pk_bf16_f32 v41, v36, v37
	v_cvt_pk_bf16_f32 v36, v114, v115
	v_cvt_pk_bf16_f32 v37, v46, v47
	s_nop 0
	v_cvt_pk_bf16_f32 v32, v98, v99
	v_cvt_pk_bf16_f32 v33, v42, v43
	ds_read_b128 v[102:105], v195 offset:16
	ds_read_b128 v[106:109], v195 offset:272
	ds_read_b128 v[110:113], v195 offset:528
	ds_read_b128 v[114:117], v195 offset:784
	v_pk_mul_f32 v[98:99], v[16:17], v[88:89] op_sel_hi:[1,0]
	v_pk_mul_f32 v[16:17], v[20:21], v[86:87] op_sel_hi:[1,0]
	v_pk_mul_f32 v[20:21], v[28:29], v[82:83] op_sel_hi:[1,0]
	v_pk_mul_f32 v[24:25], v[24:25], v[84:85] op_sel_hi:[1,0]
	s_waitcnt lgkmcnt(0)
; #define PG8_LAS __attribute__((address_space(3)))
; __device__ __forceinline__ float row_up1(float v) { return dpp_mov<0x111>(v); }
;     __device__ __forceinline__ void operator()(f32x4 (&acc)[2][2][4][2], const pg8::Unit& u, int wr, int wc, int fr, int fq) const {
;     ...
;                 {   const PG8_LAS unsigned char* wq = wl + (8 * fq + 4 * n) * 4;
;                     const f32x4 w0 = *(const PG8_LAS f32x4*)(wq), w1 = *(const PG8_LAS f32x4*)(wq + 256), w2 = *(const PG8_LAS f32x4*)(wq + 512), bb = *(const PG8_LAS f32x4*)(wq + 768);
;                     const f32x4 x0 = acc[ai][0][0][n] * rstd[0], x1 = acc[ai][0][1][n] * rstd[1], x2 = acc[ai][0][2][n] * rstd[2], x3 = acc[ai][0][3][n] * rstd[3];
;                     acc[ai][0][0][n] = x0; acc[ai][0][1][n] = x1; acc[ai][0][2][n] = x2; acc[ai][0][3][n] = x3;
;                     f32x4 p1, p2;
; #pragma unroll
;                     for (int c = 0; c < 4; ++c) { p1[c] = row_up1(x3[c]); p2[c] = row_up1(x2[c]); }
;                     g[0] = bb + w2 * x0 + w1 * p1 + w0 * p2; g[1] = bb + w2 * x1 + w1 * x0 + w0 * p1;
;                     g[2] = bb + w2 * x2 + w1 * x1 + w0 * x0; g[3] = bb + w2 * x3 + w1 * x2 + w0 * x1;
; #pragma unroll
;                     for (int m = 0; m < 4; ++m)
; #pragma unroll
;                         for (int c = 0; c < 4; ++c) g[m][c] = siluf_(g[m][c]);
;                 }
;                 __builtin_amdgcn_sched_barrier(0);
;                 {   const PG8_LAS unsigned char* wq = wl + 128 + (8 * fq + 4 * n) * 4;
;                     const f32x4 w0 = *(const PG8_LAS f32x4*)(wq), w1 = *(const PG8_LAS f32x4*)(wq + 256), w2 = *(const PG8_LAS f32x4*)(wq + 512), bb = *(const PG8_LAS f32x4*)(wq + 768);
;                     const f32x4 x0 = acc[ai][1][0][n] * rstd[0], x1 = acc[ai][1][1][n] * rstd[1], x2 = acc[ai][1][2][n] * rstd[2], x3 = acc[ai][1][3][n] * rstd[3];
;                     acc[ai][1][0][n] = x0; acc[ai][1][1][n] = x1; acc[ai][1][2][n] = x2; acc[ai][1][3][n] = x3;
;                     f32x4 p1, p2;
; #pragma unroll
;                     for (int c = 0; c < 4; ++c) { p1[c] = row_up1(x3[c]); p2[c] = row_up1(x2[c]); }
;                     g[0] *= bb + w2 * x0 + w1 * p1 + w0 * p2; g[1] *= bb + w2 * x1 + w1 * x0 + w0 * p1;
;                     g[2] *= bb + w2 * x2 + w1 * x1 + w0 * x0; g[3] *= bb + w2 * x3 + w1 * x2 + w0 * x1;
	v_pk_fma_f32 v[46:47], v[98:99], v[110:111], v[114:115]
	v_mov_b32_dpp v28, v20 row_shr:1 row_mask:0xf bank_mask:0xf bound_ctrl:1
	v_mov_b32_dpp v29, v21 row_shr:1 row_mask:0xf bank_mask:0xf bound_ctrl:1
	v_pk_mul_f32 v[100:101], v[18:19], v[88:89] op_sel_hi:[1,0]
	v_pk_mul_f32 v[18:19], v[22:23], v[86:87] op_sel_hi:[1,0]
	v_pk_mul_f32 v[22:23], v[30:31], v[82:83] op_sel_hi:[1,0]
	v_mov_b32_dpp v30, v24 row_shr:1 row_mask:0xf bank_mask:0xf bound_ctrl:1
	v_mov_b32_dpp v31, v25 row_shr:1 row_mask:0xf bank_mask:0xf bound_ctrl:1
	v_pk_fma_f32 v[46:47], v[106:107], v[28:29], v[46:47]
	v_pk_mul_f32 v[26:27], v[26:27], v[84:85] op_sel_hi:[1,0]
	v_pk_fma_f32 v[30:31], v[102:103], v[30:31], v[46:47]
	v_pk_fma_f32 v[46:47], v[16:17], v[110:111], v[114:115]
	v_mul_f32_e32 v67, 0xbfb8aa3b, v30
	v_exp_f32_e32 v67, v67
	v_mul_f32_e32 v69, 0xbfb8aa3b, v31
	v_exp_f32_e32 v69, v69
	v_mov_b32_dpp v34, v22 row_shr:1 row_mask:0xf bank_mask:0xf bound_ctrl:1
	v_mov_b32_dpp v35, v23 row_shr:1 row_mask:0xf bank_mask:0xf bound_ctrl:1
	v_pk_fma_f32 v[42:43], v[100:101], v[112:113], v[116:117]
	v_pk_fma_f32 v[46:47], v[98:99], v[106:107], v[46:47]
	v_mov_b32_dpp v38, v26 row_shr:1 row_mask:0xf bank_mask:0xf bound_ctrl:1
	v_mov_b32_dpp v39, v27 row_shr:1 row_mask:0xf bank_mask:0xf bound_ctrl:1
	v_pk_fma_f32 v[42:43], v[108:109], v[34:35], v[42:43]
	v_pk_fma_f32 v[28:29], v[102:103], v[28:29], v[46:47]
	v_pk_fma_f32 v[46:47], v[24:25], v[110:111], v[114:115]
	v_pk_fma_f32 v[110:111], v[20:21], v[110:111], v[114:115]
	v_pk_fma_f32 v[38:39], v[104:105], v[38:39], v[42:43]
	v_pk_fma_f32 v[46:47], v[16:17], v[106:107], v[46:47]
	v_pk_fma_f32 v[106:107], v[24:25], v[106:107], v[110:111]
	v_add_f32_e32 v67, 1.0, v67
	v_pk_fma_f32 v[46:47], v[98:99], v[102:103], v[46:47]
	v_pk_fma_f32 v[120:121], v[16:17], v[102:103], v[106:107]
	v_rcp_f32_e32 v102, v67
	v_add_f32_e32 v67, 1.0, v69
	v_mul_f32_e32 v69, 0xbfb8aa3b, v38
	v_exp_f32_e32 v69, v69
	v_mul_f32_e32 v71, 0xbfb8aa3b, v39
	v_pk_fma_f32 v[42:43], v[18:19], v[112:113], v[116:117]
	v_exp_f32_e32 v71, v71
	v_pk_fma_f32 v[42:43], v[100:101], v[108:109], v[42:43]
	v_rcp_f32_e32 v103, v67
	v_pk_fma_f32 v[34:35], v[104:105], v[34:35], v[42:43]
	v_pk_fma_f32 v[42:43], v[26:27], v[112:113], v[116:117]
	v_pk_fma_f32 v[112:113], v[22:23], v[112:113], v[116:117]
	v_pk_fma_f32 v[42:43], v[18:19], v[108:109], v[42:43]
	v_pk_fma_f32 v[108:109], v[26:27], v[108:109], v[112:113]
	v_add_f32_e32 v67, 1.0, v69
	v_pk_fma_f32 v[42:43], v[100:101], v[104:105], v[42:43]
	v_pk_fma_f32 v[118:119], v[18:19], v[104:105], v[108:109]
	v_rcp_f32_e32 v104, v67
	v_add_f32_e32 v67, 1.0, v71
	v_rcp_f32_e32 v105, v67
	v_mul_f32_e32 v67, 0xbfb8aa3b, v34
	v_exp_f32_e32 v67, v67
	v_mul_f32_e32 v69, 0xbfb8aa3b, v35
	v_pk_mul_f32 v[122:123], v[30:31], v[102:103]
	v_mul_f32_e32 v30, 0xbfb8aa3b, v28
	v_mul_f32_e32 v31, 0xbfb8aa3b, v29
	v_exp_f32_e32 v69, v69
	v_exp_f32_e32 v30, v30
	v_exp_f32_e32 v31, v31
	v_add_f32_e32 v67, 1.0, v67
	v_rcp_f32_e32 v102, v67
	v_add_f32_e32 v67, 1.0, v69
	v_add_f32_e32 v30, 1.0, v30
	v_add_f32_e32 v31, 1.0, v31
	v_rcp_f32_e32 v103, v67
	v_mul_f32_e32 v67, 0xbfb8aa3b, v46
	v_rcp_f32_e32 v30, v30
	v_rcp_f32_e32 v31, v31
	v_exp_f32_e32 v67, v67
	v_mul_f32_e32 v69, 0xbfb8aa3b, v47
	v_exp_f32_e32 v69, v69
	v_pk_mul_f32 v[124:125], v[28:29], v[30:31]
	v_add_f32_e32 v28, 1.0, v67
	v_mul_f32_e32 v67, 0xbfb8aa3b, v120
	v_add_f32_e32 v29, 1.0, v69
	v_exp_f32_e32 v67, v67
	v_mul_f32_e32 v69, 0xbfb8aa3b, v121
	v_mul_f32_e32 v30, 0xbfb8aa3b, v42
	v_mul_f32_e32 v31, 0xbfb8aa3b, v43
	v_exp_f32_e32 v69, v69
	v_exp_f32_e32 v30, v30
	v_exp_f32_e32 v31, v31
	v_add_f32_e32 v67, 1.0, v67
	v_rcp_f32_e32 v126, v67
	v_add_f32_e32 v67, 1.0, v69
	v_mul_f32_e32 v69, 0xbfb8aa3b, v118
	v_add_f32_e32 v30, 1.0, v30
	v_add_f32_e32 v31, 1.0, v31
	v_exp_f32_e32 v69, v69
	v_mul_f32_e32 v71, 0xbfb8aa3b, v119
	v_rcp_f32_e32 v28, v28
	v_rcp_f32_e32 v29, v29
	v_rcp_f32_e32 v30, v30
	v_rcp_f32_e32 v31, v31
	v_exp_f32_e32 v71, v71
	v_rcp_f32_e32 v127, v67
	v_add_f32_e32 v67, 1.0, v69
	v_pk_mul_f32 v[38:39], v[38:39], v[104:105]
	v_rcp_f32_e32 v148, v67
	v_add_f32_e32 v67, 1.0, v71
	v_pk_mul_f32 v[34:35], v[34:35], v[102:103]
	v_pk_mul_f32 v[46:47], v[46:47], v[28:29]
	v_pk_mul_f32 v[42:43], v[42:43], v[30:31]
	v_rcp_f32_e32 v149, v67
	ds_read_b128 v[102:105], v195 offset:144
	ds_read_b128 v[106:109], v195 offset:400
	ds_read_b128 v[110:113], v195 offset:656
	ds_read_b128 v[114:117], v195 offset:912
	v_pk_mul_f32 v[30:31], v[2:3], v[88:89] op_sel_hi:[1,0]
	v_pk_mul_f32 v[28:29], v[0:1], v[88:89] op_sel_hi:[1,0]
	v_pk_mul_f32 v[2:3], v[6:7], v[86:87] op_sel_hi:[1,0]
	v_pk_mul_f32 v[0:1], v[4:5], v[86:87] op_sel_hi:[1,0]
	v_pk_mul_f32 v[6:7], v[14:15], v[82:83] op_sel_hi:[1,0]
	v_pk_mul_f32 v[4:5], v[12:13], v[82:83] op_sel_hi:[1,0]
	v_pk_mul_f32 v[10:11], v[10:11], v[84:85] op_sel_hi:[1,0]
	v_pk_mul_f32 v[8:9], v[8:9], v[84:85] op_sel_hi:[1,0]
	v_mov_b32_dpp v12, v4 row_shr:1 row_mask:0xf bank_mask:0xf bound_ctrl:1
	v_mov_b32_dpp v13, v5 row_shr:1 row_mask:0xf bank_mask:0xf bound_ctrl:1
	v_mov_b32_dpp v82, v6 row_shr:1 row_mask:0xf bank_mask:0xf bound_ctrl:1
	v_mov_b32_dpp v83, v7 row_shr:1 row_mask:0xf bank_mask:0xf bound_ctrl:1
	v_pk_mul_f32 v[86:87], v[120:121], v[126:127]
	v_pk_mul_f32 v[88:89], v[118:119], v[148:149]
	s_waitcnt lgkmcnt(0)
; __device__ __forceinline__ unsigned pk2(float a, float b) { return pg8::cvt_pk_bf16(a, b); }
;     __device__ __forceinline__ void operator()(f32x4 (&acc)[2][2][4][2], const pg8::Unit& u, int wr, int wc, int fr, int fq) const {
;     ...
;                     g[0] *= bb + w2 * x0 + w1 * p1 + w0 * p2; g[1] *= bb + w2 * x1 + w1 * x0 + w0 * p1;
;                     g[2] *= bb + w2 * x2 + w1 * x1 + w0 * x0; g[3] *= bb + w2 * x3 + w1 * x2 + w0 * x1;
;                 }
; #pragma unroll
;                 for (int m = 0; m < 4; ++m) { pk[n][m].x = pk2(g[m][0], g[m][1]); pk[n][m].y = pk2(g[m][2], g[m][3]); }
;                 __builtin_amdgcn_sched_barrier(0);
;             }
; #pragma unroll
;             for (int m = 0; m < 4; ++m) if (fr != 0 || m >= 2) {
;                 u32x4 w; w.x = pk[0][m].x; w.y = pk[0][m].y; w.z = pk[1][m].x; w.w = pk[1][m].y;
;                 *(u32x4*)(ACT + (size_t)(tb + m) * DFF + colj) = w; }
	v_pk_fma_f32 v[118:119], v[28:29], v[110:111], v[114:115]
	v_pk_fma_f32 v[120:121], v[30:31], v[112:113], v[116:117]
	v_mov_b32_dpp v14, v8 row_shr:1 row_mask:0xf bank_mask:0xf bound_ctrl:1
	v_mov_b32_dpp v15, v9 row_shr:1 row_mask:0xf bank_mask:0xf bound_ctrl:1
	v_mov_b32_dpp v84, v10 row_shr:1 row_mask:0xf bank_mask:0xf bound_ctrl:1
	v_mov_b32_dpp v85, v11 row_shr:1 row_mask:0xf bank_mask:0xf bound_ctrl:1
	v_pk_fma_f32 v[120:121], v[108:109], v[82:83], v[120:121]
	v_pk_fma_f32 v[118:119], v[106:107], v[12:13], v[118:119]
	v_pk_fma_f32 v[84:85], v[104:105], v[84:85], v[120:121]
	v_pk_fma_f32 v[14:15], v[102:103], v[14:15], v[118:119]
	v_pk_fma_f32 v[118:119], v[2:3], v[112:113], v[116:117]
	v_pk_mul_f32 v[38:39], v[38:39], v[84:85]
	v_pk_fma_f32 v[84:85], v[0:1], v[110:111], v[114:115]
	v_pk_fma_f32 v[118:119], v[30:31], v[108:109], v[118:119]
	v_pk_fma_f32 v[84:85], v[28:29], v[106:107], v[84:85]
	v_pk_fma_f32 v[82:83], v[104:105], v[82:83], v[118:119]
	v_pk_fma_f32 v[12:13], v[102:103], v[12:13], v[84:85]
	v_pk_mul_f32 v[34:35], v[34:35], v[82:83]
	v_pk_fma_f32 v[82:83], v[8:9], v[110:111], v[114:115]
	v_pk_fma_f32 v[84:85], v[10:11], v[112:113], v[116:117]
	v_pk_fma_f32 v[82:83], v[0:1], v[106:107], v[82:83]
	v_pk_fma_f32 v[84:85], v[2:3], v[108:109], v[84:85]
	v_pk_fma_f32 v[82:83], v[28:29], v[102:103], v[82:83]
	v_pk_fma_f32 v[84:85], v[30:31], v[104:105], v[84:85]
	v_pk_mul_f32 v[82:83], v[46:47], v[82:83]
	v_pk_mul_f32 v[84:85], v[42:43], v[84:85]
	v_pk_fma_f32 v[42:43], v[4:5], v[110:111], v[114:115]
	v_pk_fma_f32 v[46:47], v[6:7], v[112:113], v[116:117]
	v_pk_fma_f32 v[42:43], v[8:9], v[106:107], v[42:43]
	v_pk_fma_f32 v[46:47], v[10:11], v[108:109], v[46:47]
	v_pk_fma_f32 v[42:43], v[0:1], v[102:103], v[42:43]
	v_pk_fma_f32 v[46:47], v[2:3], v[104:105], v[46:47]
	v_pk_mul_f32 v[14:15], v[122:123], v[14:15]
	v_pk_mul_f32 v[12:13], v[124:125], v[12:13]
	v_pk_mul_f32 v[88:89], v[88:89], v[46:47]
	v_pk_mul_f32 v[86:87], v[86:87], v[42:43]
	v_cvt_pk_bf16_f32 v46, v14, v15
	v_cvt_pk_bf16_f32 v47, v38, v39
	v_cvt_pk_bf16_f32 v42, v12, v13
	v_cvt_pk_bf16_f32 v43, v34, v35
	v_cvt_pk_bf16_f32 v38, v82, v83
	v_cvt_pk_bf16_f32 v39, v84, v85
	s_nop 0
	v_cvt_pk_bf16_f32 v34, v86, v87
	v_cvt_pk_bf16_f32 v35, v88, v89
	s_and_saveexec_b64 s[8:9], s[0:1]
	s_cbranch_execz .LBB0_756
	v_mov_b64_e32 v[12:13], s[22:23]
	v_mad_i64_i32 v[14:15], s[10:11], v66, s56, v[12:13]
	v_mad_i64_i32 v[12:13], s[10:11], v68, s56, v[12:13]
	v_lshl_add_u64 v[14:15], v[14:15], 0, v[64:65]
	v_lshl_add_u64 v[12:13], v[12:13], 0, v[64:65]
	global_store_dwordx4 v[14:15], v[44:47], off
	global_store_dwordx4 v[12:13], v[40:43], off
